# fused tail: dropped the final vmcnt(0) wait and barrier before s_endpgm (waves end as soon as their stores are issued)
# speedup vs baseline: 1.0035x; 1.0021x over previous
.LBB0_1498:
	s_endpgm
.LBB0_1499:
	s_endpgm
	.section	.rodata,"a",@progbits
	.p2align	6, 0x0
